# v27
# speedup vs baseline: 1.0042x; 1.0042x over previous
.LBB0_844:
	v_lshlrev_b32_e32 v12, 4, v0
	global_load_dwordx4 v[4:7], v12, s[14:15]
	global_load_dwordx4 v[8:11], v12, s[16:17]
	s_waitcnt vmcnt(0)
	v_max3_f32 v2, |v4|, |v5|, |v6|
	v_max3_f32 v1, |v8|, |v9|, |v10|
	v_max_f32_e64 v2, v2, |v7|
	v_max_f32_e64 v1, v1, |v11|
	s_nop 1
	v_max_f32_dpp v2, v2, v2 quad_perm:[1,0,3,2] row_mask:0xf bank_mask:0xf
	v_max_f32_dpp v1, v1, v1 quad_perm:[1,0,3,2] row_mask:0xf bank_mask:0xf
	s_nop 1
	v_max_f32_dpp v2, v2, v2 quad_perm:[2,3,0,1] row_mask:0xf bank_mask:0xf
	v_max_f32_dpp v1, v1, v1 quad_perm:[2,3,0,1] row_mask:0xf bank_mask:0xf
	s_nop 1
	v_max_f32_dpp v2, v2, v2 row_half_mirror row_mask:0xf bank_mask:0xf
	v_max_f32_dpp v1, v1, v1 row_half_mirror row_mask:0xf bank_mask:0xf
	s_nop 1
	v_max_f32_dpp v2, v2, v2 row_mirror row_mask:0xf bank_mask:0xf
	v_max_f32_dpp v1, v1, v1 row_mirror row_mask:0xf bank_mask:0xf
	v_mov_b32_e32 v13, v2
	v_mov_b32_e32 v14, v1
	s_nop 1
	v_permlane16_swap_b32_e32 v2, v13
	v_permlane16_swap_b32_e32 v1, v14
	s_nop 0
	v_max_f32_e32 v2, v2, v13
	v_max_f32_e32 v1, v1, v14
	v_mov_b32_e32 v13, v2
	v_mov_b32_e32 v14, v1
	s_nop 1
	v_permlane32_swap_b32_e32 v2, v13
	v_permlane32_swap_b32_e32 v1, v14
	s_nop 0
	v_max_f32_e32 v2, v2, v13
	v_max_f32_e32 v1, v1, v14
	v_mul_f32_e32 v2, 0x41b8aa3b, v2
	v_mul_f32_e32 v1, v1, v2
	s_mov_b32 s47, s2
	s_cmpk_gt_i32 s47, 0x7ff
	v_readfirstlane_b32 s16, v1
	s_cbranch_scc1 .LBB0_851
	s_lshl_b32 s6, s52, 24
	s_add_u32 s14, s10, 0x12000000
	s_addc_u32 s15, s11, 0
	s_add_u32 s17, s10, s6
	s_addc_u32 s18, s11, 0
	s_add_u32 s56, s17, 0x6800000
	s_addc_u32 s57, s18, 0
	v_and_b32_e32 v9, 64, v252
	s_add_u32 s58, s17, 0x4800000
	v_xor_b32_e32 v8, 32, v252
	v_add_u32_e32 v9, 64, v9
	v_or_b32_e32 v1, s33, v0
	s_addc_u32 s59, s18, 0
	s_lshl_b32 s36, s52, 8
	v_cmp_lt_i32_e32 vcc, v8, v9
	v_bfe_u32 v5, v0, 5, 1
	v_and_b32_e32 v7, 31, v0
	v_ashrrev_i32_e32 v6, 2, v1
	s_movk_i32 s17, 0xffe0
	v_cndmask_b32_e32 v8, v252, v8, vcc
	s_lshl_b64 s[18:19], s[36:37], 2
	v_ashrrev_i32_e32 v3, 6, v1
	v_and_b32_e32 v200, 0xffffffe0, v6
	v_bfi_b32 v207, s17, v6, v0
	v_lshlrev_b32_e32 v6, 3, v5
	v_lshlrev_b32_e32 v215, 2, v8
	s_add_u32 s4, s4, s18
	v_mul_u32_u24_e32 v8, 0x210, v7
	v_lshlrev_b32_e32 v5, 4, v5
	s_addc_u32 s5, s5, s19
	v_and_b32_e32 v208, 32, v0
	v_add3_u32 v228, 0, v8, v5
	v_lshlrev_b32_e32 v5, 7, v3
	v_lshl_add_u64 v[202:203], s[4:5], 0, v[208:209]
	v_lshlrev_b32_e32 v14, 4, v252
	global_load_dwordx4 v[10:13], v14, s[4:5]
	v_add_u32_e32 v14, 0x1f000, v14
	v_add_u32_e32 v202, 0x1f000, v208
	s_waitcnt vmcnt(0)
	ds_write_b128 v14, v[10:13]
	s_waitcnt lgkmcnt(0)
	s_barrier
	v_and_b32_e32 v5, 0x80, v5
	s_movk_i32 s4, 0x2200
	v_ashrrev_i32_e32 v196, 3, v1
	v_ashrrev_i32_e32 v198, 5, v1
	v_lshlrev_b32_e32 v4, 3, v1
	v_mul_lo_u32 v3, v3, s4
	v_lshlrev_b32_e32 v1, 4, v1
	v_lshlrev_b32_e32 v208, 1, v5
	v_add_u32_e32 v3, 0, v3
	s_movk_i32 s4, 0x110
	v_and_b32_e32 v8, 0xf0, v1
	v_lshl_add_u64 v[10:11], s[10:11], 0, v[208:209]
	v_mov_b32_e32 v9, v209
	v_ashrrev_i32_e32 v199, 31, v198
	v_or_b32_e32 v14, v5, v7
	v_mad_u32_u24 v7, v7, s4, v3
	v_add_u32_e32 v1, v3, v8
	v_lshl_add_u64 v[8:9], v[10:11], 0, v[8:9]
	s_mov_b64 s[4:5], 0x2a000000
	v_lshl_add_u64 v[204:205], v[8:9], 0, s[4:5]
	v_mul_u32_u24_e32 v5, 0x90, v14
	v_lshlrev_b64 v[8:9], 11, v[198:199]
	v_bitop3_b32 v14, v0, 31, s33 bitop3:0xc8
	v_bfe_u32 v206, v0, 4, 2
	s_movk_i32 s4, 0x210
	v_lshl_or_b32 v8, v14, 4, v8
	v_ashrrev_i32_e32 v197, 31, v196
	v_and_b32_e32 v2, 56, v4
	v_and_b32_e32 v4, 0xf8, v4
	v_add3_u32 v229, 0, v5, v6
	v_mul_lo_u32 v5, v198, s4
	s_movk_i32 s4, 0x90
	v_or_b32_e32 v214, 4, v206
	v_lshl_add_u64 v[216:217], s[10:11], 0, v[8:9]
	v_lshlrev_b64 v[8:9], 14, v[196:197]
	v_bitop3_b32 v0, v0, 7, s33 bitop3:0xc8
	v_lshl_add_u32 v12, v4, 1, 0
	v_lshl_add_u32 v13, v2, 1, 0
	s_xor_b32 s16, s16, 0x80000000
	v_mul_u32_u24_e32 v3, 0x110, v206
	v_mul_lo_u32 v10, v196, s4
	v_mul_u32_u24_e32 v11, 0x110, v214
	v_lshl_or_b32 v8, v0, 4, v8
	s_mov_b32 s7, s37
	v_ashrrev_i32_e32 v201, 31, v200
	s_mov_b32 s17, s16
	s_mov_b32 s18, s16
	s_mov_b32 s19, s16
	s_mov_b32 s20, s16
	s_mov_b32 s21, s16
	s_mov_b32 s22, s16
	s_mov_b32 s23, s16
	s_mov_b32 s24, s16
	s_mov_b32 s25, s16
	s_mov_b32 s26, s16
	s_mov_b32 s27, s16
	s_mov_b32 s28, s16
	s_mov_b32 s29, s16
	s_mov_b32 s30, s16
	s_mov_b32 s31, s16
	s_lshl_b32 s53, s47, 4
	v_lshl_add_u64 v[218:219], s[10:11], 0, v[8:9]
	v_lshlrev_b32_e32 v208, 1, v4
	v_lshlrev_b32_e32 v220, 1, v2
	v_lshlrev_b32_e32 v222, 1, v6
	v_add_u32_e32 v197, v7, v6
	v_add_u32_e32 v230, v1, v3
	v_add_u32_e32 v231, v1, v11
	v_add_u32_e32 v232, v12, v5
	v_add_u32_e32 v233, v13, v10
